# attention work queue: next unit index prefetched (returning atomic issued right after the current unit is obtained)
# speedup vs baseline: 1.0040x; 1.0040x over previous
; #define LAS __attribute__((address_space(3)))
; __device__ __forceinline__ int lane_id() { int l = __builtin_amdgcn_mbcnt_hi(~0u, __builtin_amdgcn_mbcnt_lo(~0u, 0u)); asm volatile("" : "+v"(l)); return l; }
; __device__ __forceinline__ void attn_phase(LAS unsigned char* lds, const AttnArgs& T, const float* relb, const int wave) {
;     const int lane = lane_id(), tid = wave * 64 + lane;
;     LAS float* ext = (LAS float*)(lds + AL_EXT);
;     for (int i = tid; i < 8 * 832; i += NWAVES * 64) { const int h = i / 832, k = i % 832; ext[i] = relb[h * 513 + (k < 512 ? k : 512)] * LOG2E; }
;     volatile LAS unsigned* uw = (volatile LAS unsigned*)(lds + AL_UNIT);
;     int qcur = (int)(blockIdx.x & 7u), qleft = 8;
;     for (;;) {
.LBB0_332:
	s_or_b64 exec, exec, s[6:7]
	s_add_u32 s5, s44, 0x14e80000
	s_addc_u32 s84, s45, 0
	s_add_u32 s80, s44, 0xba00000
	v_readlane_b32 s14, v249, 0
	s_addc_u32 s81, s45, 0
	s_lshl_b32 s0, s14, 13
	s_add_i32 s92, s0, 0
	s_lshl_b32 s0, s14, 4
	s_and_b32 s1, s0, 0x3fffffc0
	s_lshl_b32 s0, s50, 2
	s_add_i32 s93, s0, 0
	s_and_b32 s31, s38, 7
	s_ashr_i32 s51, s50, 31
	s_add_i32 s93, s93, 0x16800
	s_lshl_b32 s2, s1, 1
	s_add_u32 s0, s80, s2
	v_writelane_b32 v249, s1, 56
	s_addc_u32 s1, s81, 0
	s_add_u32 s8, s44, s2
	s_addc_u32 s9, s45, 0
	s_add_u32 s62, s8, 0x1d180000
	s_addc_u32 s61, s9, 0
	s_lshl_b64 s[28:29], s[50:51], 1
	s_add_u32 s12, s80, s28
	s_addc_u32 s13, s81, s29
	s_add_u32 s10, s44, s28
	s_addc_u32 s30, s45, s29
	s_add_u32 s2, s10, 0x1b180000
	s_addc_u32 s3, s30, 0
	s_add_u32 s60, s5, s28
	s_mul_i32 s4, s14, 0xd00
	v_writelane_b32 v249, s28, 57
	s_addc_u32 s63, s84, s29
	s_lshl_b32 s14, s14, 2
	s_add_u32 s14, s44, s14
	s_addc_u32 s15, s45, 0
	s_add_u32 s14, s14, 0xc8400
	s_addc_u32 s15, s15, 0
	v_writelane_b32 v249, s29, 58
	s_add_u32 s68, s8, 0x1d280000
	s_addc_u32 s69, s9, 0
	v_writelane_b32 v249, s50, 59
	s_lshl_b64 s[28:29], s[50:51], 2
	s_add_u32 s8, s44, s28
	v_writelane_b32 v249, s51, 60
	v_writelane_b32 v249, s28, 61
	s_addc_u32 s9, s45, s29
	v_cmp_eq_u32_e64 s[6:7], 0, v0
	v_writelane_b32 v249, s29, 62
	s_add_u32 s28, s8, 0xc9500
	s_addc_u32 s29, s9, 0
	v_add_u32_e32 v0, 64, v167
	s_add_u32 s70, s10, 0x1c180000
	v_cmp_lt_i32_e32 vcc, v166, v0
	s_addc_u32 s71, s30, 0
	s_add_u32 s40, s8, 0xc8500
	v_cndmask_b32_e32 v1, v196, v166, vcc
	v_cmp_lt_i32_e32 vcc, v143, v0
	s_addc_u32 s41, s9, 0
	s_add_i32 s4, s4, 0
	v_cndmask_b32_e32 v0, v196, v143, vcc
	s_add_i32 s77, 0, 0x17000
	s_mov_b32 s11, 0
	v_lshlrev_b32_e32 v197, 2, v1
	v_lshlrev_b32_e32 v198, 2, v0
	v_writelane_b32 v249, s4, 50
	v_mov_b32_e32 v184, 8
	v_mov_b32_e32 v185, s31
	v_mov_b32_e32 v1, 0
	v_mov_b32_e32 v186, 1
	s_movk_i32 s76, 0x84
	s_movk_i32 s85, 0x1200
	s_add_i32 s95, s92, 0x400
	s_add_i32 s96, s92, 0x800
	s_add_i32 s97, s92, 0xc00
	s_add_i32 s91, s92, 0x1000
	s_add_i32 s72, s92, 0x1400
	s_add_i32 s73, s92, 0x1800
	s_add_i32 s4, s92, 0x1c00
	s_movk_i32 s86, 0x900
	v_mov_b32_e32 v187, 0x358637bd
	v_mov_b32_e32 v188, s77
	v_mov_b32_e32 v189, 0x1200
	v_writelane_b32 v249, s31, 48
	s_mov_b32 s32, 0
	s_branch .LBB0_335

; __device__ __forceinline__ void attn_phase(LAS unsigned char* lds, const AttnArgs& T, const float* relb, const int wave) {
;     ...
;     for (;;) {
;         __syncthreads();
;         if (tid == 0) {
;             unsigned code = 0xffffffffu;
;             while (qleft > 0) {
;                 const unsigned j = __hip_atomic_fetch_add(T.ctr + 16 * qcur, 1u, __ATOMIC_RELAXED, __HIP_MEMORY_SCOPE_AGENT);
;                 if (j < 132u) { code = (unsigned)qcur * 132u + j; break; }
;     ...
;             }
;             uw[0] = code;
;         }
;         __syncthreads();
;         const unsigned u = (unsigned)__builtin_amdgcn_readfirstlane((int)uw[0]);
;         if (u == 0xffffffffu) break;
;         const int qq = (int)(u / 132u), j = (int)(u % 132u);
;         if (j < 66) attn_unit<true>(lds, T, qq * 66 + j, wave, lane); else attn_unit<false>(lds, T, qq * 66 + j - 66, wave, lane);
.LBB0_339:
	v_cmp_lt_i32_e32 vcc, 0, v184
	s_or_b64 s[42:43], s[42:43], exec
	s_and_saveexec_b64 s[52:53], vcc
	s_cbranch_execz .LBB0_338
	s_cmp_eq_u32 s32, 1
	s_cbranch_scc0 .Laqa_sync
	s_mov_b32 s32, 0
	s_waitcnt vmcnt(0)
	v_mov_b32_e32 v0, v250
	s_branch .Laqa_got
.Laqa_sync:
	v_lshlrev_b32_e32 v0, 4, v185
	v_lshl_add_u64 v[4:5], v[0:1], 2, s[44:45]
	global_atomic_add v0, v[4:5], v186, off sc0
	s_waitcnt vmcnt(0)
.Laqa_got:
	v_cmp_gt_u32_e32 vcc, s76, v0
	s_and_saveexec_b64 s[36:37], vcc
	s_xor_b64 s[54:55], exec, s[36:37]
	v_mad_u64_u32 v[2:3], s[36:37], v185, s76, v[0:1]
	s_andn2_saveexec_b64 s[54:55], s[54:55]
	s_cbranch_execz .LBB0_337
	v_add_u32_e32 v0, 1, v185
	v_and_b32_e32 v185, 7, v0
	v_add_u32_e32 v184, -1, v184
	s_branch .LBB0_337
.LBB0_344:
	s_or_b64 exec, exec, s[30:31]
	v_mov_b32_e32 v0, s77
	ds_write_b32 v0, v2
	v_cmp_ne_u32_e32 vcc, -1, v2
	s_cbranch_vccz .Laqa_nopf
	v_lshlrev_b32_e32 v0, 4, v185
	v_lshl_add_u64 v[4:5], v[0:1], 2, s[44:45]
	global_atomic_add v250, v[4:5], v186, off sc0
	s_mov_b32 s32, 1
.Laqa_nopf:
.LBB0_345:
	s_or_b64 exec, exec, s[8:9]
	s_waitcnt lgkmcnt(0)
	s_barrier
	ds_read_b32 v0, v188
	s_waitcnt lgkmcnt(0)
	v_readfirstlane_b32 s78, v0
	s_cmp_eq_u32 s78, -1
	s_cbranch_scc1 .LBB0_370
	s_mul_hi_u32 s8, s78, 0x3e0f83e1
	s_lshr_b32 s79, s8, 5
	s_mul_i32 s8, s79, 0x84
	s_sub_i32 s8, s78, s8
	s_mul_i32 s87, s79, 0x42
	s_add_i32 s87, s87, s8
	s_cmpk_gt_u32 s8, 0x41
	s_mov_b64 s[8:9], -1
	s_cbranch_scc0 .LBB0_380
	s_add_i32 s10, s87, 0xffffffbe
	s_cmpk_gt_u32 s10, 0x1ff
	s_cselect_b64 s[8:9], -1, 0
	s_min_u32 s30, s10, 0x1ff
	s_and_b32 s36, s30, 0xff
	v_mov_b32_e32 v183, v196
	s_cmpk_lt_u32 s10, 0x200
	s_mov_b64 s[30:31], -1
	s_cbranch_scc0 .LBB0_349
	s_and_b32 s10, s10, 0x100
	s_or_b32 s10, s36, s10
	s_lshl_b32 s54, s10, 6
	s_mov_b64 s[30:31], 0

; #define PG8_BAR __builtin_amdgcn_s_barrier()
; template <int KK, class Epi, class Sched, bool ALIGN_EPI = true>
; __device__ __forceinline__ void gemm_phase(LAS unsigned char* lds, const bf16* gA, const bf16* gBt, const Sched& S, const Epi& E, const int wid) {
;     ...
;         if constexpr (ALIGN_EPI) { if (wr == 0) PG8_BAR; }
;         E(acc, cur, wr, wc, fr, fq);
;         if (!has_next) break;
; #pragma unroll
;         for (int a = 0; a < 2; ++a)
; #pragma unroll
;             for (int b = 0; b < 2; ++b)
; #pragma unroll
;                 for (int m = 0; m < 4; ++m)
; #pragma unroll
;                     for (int n = 0; n < 2; ++n) acc[a][b][m][n] = (f32x4){0.f, 0.f, 0.f, 0.f};
;         cur = nxt; cA = nA; cB = nB; ++ui;
;         if constexpr (ALIGN_EPI) { if (wr == 1) PG8_BAR; }
;     }
.LBB0_674:
	s_cmp_lg_u32 s64, 0x100
	s_cbranch_scc1 .Lp5a_epi
	s_cmp_lg_u32 s41, 3
	s_cbranch_scc1 .Lp5a_epi
	s_cmp_gt_u32 s86, 63
	s_cbranch_scc1 .Lp5a_epi
	s_bfe_u32 s32, s86, 0x20003
	s_and_b32 s90, s86, 7
	s_lshl_b32 s90, s90, 1
	s_bfe_u32 s88, s86, 0x10005
	s_add_i32 s90, s90, s88
	v_readlane_b32 s88, v249, 0
	v_lshlrev_b32_e32 v140, 4, v196
	s_nop 1
	s_lshl_b32 s89, s88, 10
	v_add_u32_e32 v140, s89, v140
	s_mul_i32 s89, s90, 3
	s_lshl_b32 s89, s89, 18
	s_add_u32 s76, s46, s89
	s_addc_u32 s77, s47, 0
	s_add_u32 s76, s76, 0x0
	s_addc_u32 s77, s77, 0
	s_cmp_eq_u32 s32, 0
	s_cbranch_scc1 .Lp5a_cons
	s_add_i32 s89, s32, -1
	s_lshl_b32 s89, s89, 18
	s_add_u32 s76, s76, s89
	s_addc_u32 s77, s77, 0
	s_nop 7
	global_store_dwordx4 v140, v[0:3], s[76:77] sc0 sc1
	s_add_u32 s76, s76, 0x2000
	s_addc_u32 s77, s77, 0
	global_store_dwordx4 v140, v[4:7], s[76:77] sc0 sc1
	s_add_u32 s76, s76, 0x2000
	s_addc_u32 s77, s77, 0
	global_store_dwordx4 v140, v[8:11], s[76:77] sc0 sc1
	s_add_u32 s76, s76, 0x2000
	s_addc_u32 s77, s77, 0
	global_store_dwordx4 v140, v[12:15], s[76:77] sc0 sc1
	s_add_u32 s76, s76, 0x2000
	s_addc_u32 s77, s77, 0
	global_store_dwordx4 v140, v[16:19], s[76:77] sc0 sc1
	s_add_u32 s76, s76, 0x2000
	s_addc_u32 s77, s77, 0
	global_store_dwordx4 v140, v[20:23], s[76:77] sc0 sc1
	s_add_u32 s76, s76, 0x2000
	s_addc_u32 s77, s77, 0
	global_store_dwordx4 v140, v[24:27], s[76:77] sc0 sc1
	s_add_u32 s76, s76, 0x2000
	s_addc_u32 s77, s77, 0
	global_store_dwordx4 v140, v[28:31], s[76:77] sc0 sc1
	s_add_u32 s76, s76, 0x2000
	s_addc_u32 s77, s77, 0
	global_store_dwordx4 v140, v[32:35], s[76:77] sc0 sc1
	s_add_u32 s76, s76, 0x2000
	s_addc_u32 s77, s77, 0
	global_store_dwordx4 v140, v[36:39], s[76:77] sc0 sc1
	s_add_u32 s76, s76, 0x2000
	s_addc_u32 s77, s77, 0
	global_store_dwordx4 v140, v[40:43], s[76:77] sc0 sc1
	s_add_u32 s76, s76, 0x2000
	s_addc_u32 s77, s77, 0
	global_store_dwordx4 v140, v[44:47], s[76:77] sc0 sc1
	s_add_u32 s76, s76, 0x2000
	s_addc_u32 s77, s77, 0
	global_store_dwordx4 v140, v[48:51], s[76:77] sc0 sc1
	s_add_u32 s76, s76, 0x2000
	s_addc_u32 s77, s77, 0
	global_store_dwordx4 v140, v[52:55], s[76:77] sc0 sc1
	s_add_u32 s76, s76, 0x2000
	s_addc_u32 s77, s77, 0
	global_store_dwordx4 v140, v[56:59], s[76:77] sc0 sc1
	s_add_u32 s76, s76, 0x2000
	s_addc_u32 s77, s77, 0
	global_store_dwordx4 v140, v[60:63], s[76:77] sc0 sc1
	s_add_u32 s76, s76, 0x2000
	s_addc_u32 s77, s77, 0
	global_store_dwordx4 v140, v[64:67], s[76:77] sc0 sc1
	s_add_u32 s76, s76, 0x2000
	s_addc_u32 s77, s77, 0
	global_store_dwordx4 v140, v[68:71], s[76:77] sc0 sc1
	s_add_u32 s76, s76, 0x2000
	s_addc_u32 s77, s77, 0
	global_store_dwordx4 v140, v[72:75], s[76:77] sc0 sc1
	s_add_u32 s76, s76, 0x2000
	s_addc_u32 s77, s77, 0
	global_store_dwordx4 v140, v[76:79], s[76:77] sc0 sc1
	s_add_u32 s76, s76, 0x2000
	s_addc_u32 s77, s77, 0
	global_store_dwordx4 v140, v[80:83], s[76:77] sc0 sc1
	s_add_u32 s76, s76, 0x2000
	s_addc_u32 s77, s77, 0
	global_store_dwordx4 v140, v[84:87], s[76:77] sc0 sc1
	s_add_u32 s76, s76, 0x2000
	s_addc_u32 s77, s77, 0
	global_store_dwordx4 v140, v[88:91], s[76:77] sc0 sc1
	s_add_u32 s76, s76, 0x2000
	s_addc_u32 s77, s77, 0
	global_store_dwordx4 v140, v[92:95], s[76:77] sc0 sc1
	s_add_u32 s76, s76, 0x2000
	s_addc_u32 s77, s77, 0
	global_store_dwordx4 v140, v[96:99], s[76:77] sc0 sc1
	s_add_u32 s76, s76, 0x2000
	s_addc_u32 s77, s77, 0
	global_store_dwordx4 v140, v[100:103], s[76:77] sc0 sc1
	s_add_u32 s76, s76, 0x2000
	s_addc_u32 s77, s77, 0
	global_store_dwordx4 v140, v[104:107], s[76:77] sc0 sc1
	s_add_u32 s76, s76, 0x2000
	s_addc_u32 s77, s77, 0
	global_store_dwordx4 v140, v[108:111], s[76:77] sc0 sc1
	s_add_u32 s76, s76, 0x2000
	s_addc_u32 s77, s77, 0
	global_store_dwordx4 v140, v[112:115], s[76:77] sc0 sc1
	s_add_u32 s76, s76, 0x2000
	s_addc_u32 s77, s77, 0
	global_store_dwordx4 v140, v[116:119], s[76:77] sc0 sc1
	s_add_u32 s76, s76, 0x2000
	s_addc_u32 s77, s77, 0
	global_store_dwordx4 v140, v[120:123], s[76:77] sc0 sc1
	s_add_u32 s76, s76, 0x2000
	s_addc_u32 s77, s77, 0
	global_store_dwordx4 v140, v[124:127], s[76:77] sc0 sc1
	s_waitcnt vmcnt(0)
	s_lshl_b32 s89, s90, 2
	s_add_i32 s89, s89, s32
	s_lshl_b32 s89, s89, 2
	v_mov_b32_e32 v141, s89
	v_mov_b32_e32 v142, 1
	s_mov_b64 s[78:79], exec
	s_mov_b64 exec, 1
	global_atomic_add v141, v142, s[44:45] offset:3200
	s_mov_b64 exec, s[78:79]
	s_branch .LBB0_677

; #define LAS __attribute__((address_space(3)))
; __device__ __forceinline__ int lane_id() { int l = __builtin_amdgcn_mbcnt_hi(~0u, __builtin_amdgcn_mbcnt_lo(~0u, 0u)); asm volatile("" : "+v"(l)); return l; }
; __device__ __forceinline__ void attn_phase(LAS unsigned char* lds, const AttnArgs& T, const float* relb, const int wave) {
;     const int lane = lane_id(), tid = wave * 64 + lane;
;     LAS float* ext = (LAS float*)(lds + AL_EXT);
;     for (int i = tid; i < 8 * 832; i += NWAVES * 64) { const int h = i / 832, k = i % 832; ext[i] = relb[h * 513 + (k < 512 ? k : 512)] * LOG2E; }
;     volatile LAS unsigned* uw = (volatile LAS unsigned*)(lds + AL_UNIT);
;     int qcur = (int)(blockIdx.x & 7u), qleft = 8;
;     for (;;) {
.LBB0_1068:
	s_or_b64 exec, exec, s[6:7]
	s_add_u32 s50, s20, 0x14e80000
	s_addc_u32 s51, s21, 0
	s_add_u32 s5, s20, 0xba00000
	v_readlane_b32 s0, v249, 56
	s_addc_u32 s29, s21, 0
	s_lshl_b32 s2, s0, 1
	s_add_u32 s0, s5, s2
	s_addc_u32 s1, s29, 0
	s_add_u32 s8, s20, s2
	s_addc_u32 s9, s21, 0
	s_add_u32 s2, s8, 0x1d200000
	s_addc_u32 s3, s9, 0
	v_readlane_b32 s14, v249, 57
	v_readlane_b32 s15, v249, 58
	s_add_u32 s12, s5, s14
	s_addc_u32 s13, s29, s15
	s_add_u32 s10, s20, s14
	s_addc_u32 s24, s21, s15
	s_add_u32 s18, s10, 0x1b980000
	s_addc_u32 s19, s24, 0
	s_add_u32 s40, s50, s14
	v_readlane_b32 s14, v249, 0
	s_addc_u32 s41, s51, s15
	s_lshl_b32 s14, s14, 2
	s_add_u32 s14, s20, s14
	s_addc_u32 s15, s21, 0
	s_add_u32 s14, s14, 0xc8420
	s_addc_u32 s15, s15, 0
	s_add_u32 s52, s8, 0x1d300000
	s_addc_u32 s53, s9, 0
	v_readlane_b32 s8, v249, 61
	v_readlane_b32 s9, v249, 62
	s_add_u32 s8, s20, s8
	s_addc_u32 s9, s21, s9
	s_add_u32 s16, s8, 0xc9d00
	s_addc_u32 s17, s9, 0
	s_add_u32 s54, s10, 0x1c980000
	s_addc_u32 s55, s24, 0
	s_add_u32 s24, s8, 0xc8d00
	s_addc_u32 s25, s9, 0
	v_readlane_b32 s8, v249, 48
	s_add_i32 s57, 0, 0x17000
	s_mov_b32 s11, 0
	v_cmp_eq_u32_e64 s[6:7], 0, v0
	v_mov_b32_e32 v192, 8
	v_mov_b32_e32 v193, s8
	v_mov_b32_e32 v1, 0
	v_mov_b32_e32 v194, 1
	s_movk_i32 s56, 0x84
	s_movk_i32 s58, 0x1200
	s_movk_i32 s59, 0x900
	v_mov_b32_e32 v195, 0x358637bd
	v_mov_b32_e32 v199, s57
	v_mov_b32_e32 v200, 0x1200
	s_mov_b32 s71, 0
	s_branch .LBB0_1071

; __device__ __forceinline__ void attn_phase(LAS unsigned char* lds, const AttnArgs& T, const float* relb, const int wave) {
;     ...
;     for (;;) {
;         __syncthreads();
;         if (tid == 0) {
;             unsigned code = 0xffffffffu;
;             while (qleft > 0) {
;                 const unsigned j = __hip_atomic_fetch_add(T.ctr + 16 * qcur, 1u, __ATOMIC_RELAXED, __HIP_MEMORY_SCOPE_AGENT);
;                 if (j < 132u) { code = (unsigned)qcur * 132u + j; break; }
;     ...
;             }
;             uw[0] = code;
;         }
;         __syncthreads();
;         const unsigned u = (unsigned)__builtin_amdgcn_readfirstlane((int)uw[0]);
;         if (u == 0xffffffffu) break;
;         const int qq = (int)(u / 132u), j = (int)(u % 132u);
;         if (j < 66) attn_unit<true>(lds, T, qq * 66 + j, wave, lane); else attn_unit<false>(lds, T, qq * 66 + j - 66, wave, lane);
.LBB0_1075:
	v_cmp_lt_i32_e32 vcc, 0, v192
	s_or_b64 s[30:31], s[30:31], exec
	s_and_saveexec_b64 s[36:37], vcc
	s_cbranch_execz .LBB0_1074
	s_cmp_eq_u32 s71, 1
	s_cbranch_scc0 .Laqb_sync
	s_mov_b32 s71, 0
	s_waitcnt vmcnt(0)
	v_mov_b32_e32 v0, v250
	s_branch .Laqb_got
.Laqb_sync:
	v_lshlrev_b32_e32 v0, 4, v193
	v_lshl_add_u64 v[4:5], v[0:1], 2, s[20:21]
	global_atomic_add v0, v[4:5], v194, off offset:512 sc0
	s_waitcnt vmcnt(0)
.Laqb_got:
	v_cmp_gt_u32_e32 vcc, s56, v0
	s_and_saveexec_b64 s[38:39], vcc
	s_xor_b64 s[38:39], exec, s[38:39]
	v_mad_u64_u32 v[2:3], s[42:43], v193, s56, v[0:1]
	s_andn2_saveexec_b64 s[38:39], s[38:39]
	s_cbranch_execz .LBB0_1073
	v_add_u32_e32 v0, 1, v193
	v_and_b32_e32 v193, 7, v0
	v_add_u32_e32 v192, -1, v192
	s_branch .LBB0_1073
.LBB0_1080:
	s_or_b64 exec, exec, s[26:27]
	v_mov_b32_e32 v0, s57
	ds_write_b32 v0, v2
	v_cmp_ne_u32_e32 vcc, -1, v2
	s_cbranch_vccz .Laqb_nopf
	v_lshlrev_b32_e32 v0, 4, v193
	v_lshl_add_u64 v[4:5], v[0:1], 2, s[20:21]
	global_atomic_add v250, v[4:5], v194, off offset:512 sc0
	s_mov_b32 s71, 1
.Laqb_nopf:
.LBB0_1081:
	s_or_b64 exec, exec, s[8:9]
	s_waitcnt lgkmcnt(0)
	s_barrier
	ds_read_b32 v0, v199
	s_waitcnt lgkmcnt(0)
	v_readfirstlane_b32 s48, v0
	s_cmp_eq_u32 s48, -1
	s_cbranch_scc1 .LBB0_1106
	s_mul_hi_u32 s8, s48, 0x3e0f83e1
	s_lshr_b32 s49, s8, 5
	s_mul_i32 s8, s49, 0x84
	s_sub_i32 s8, s48, s8
	s_mul_i32 s60, s49, 0x42
	s_add_i32 s60, s60, s8
	s_cmpk_gt_u32 s8, 0x41
	s_mov_b64 s[8:9], -1
	s_cbranch_scc0 .LBB0_1116
	s_add_i32 s10, s60, 0xffffffbe
	s_cmpk_gt_u32 s10, 0x1ff
	s_cselect_b64 s[8:9], -1, 0
	s_min_u32 s26, s10, 0x1ff
	s_and_b32 s31, s26, 0xff
	v_mov_b32_e32 v183, v196
	s_cmpk_lt_u32 s10, 0x200
	s_mov_b64 s[26:27], -1
	s_cbranch_scc0 .LBB0_1085
	s_and_b32 s10, s10, 0x100
	s_or_b32 s10, s31, s10
	s_lshl_b32 s38, s10, 6
	s_mov_b64 s[26:27], 0

; #define PG8_BAR __builtin_amdgcn_s_barrier()
; template <int KK, class Epi, class Sched, bool ALIGN_EPI = true>
; __device__ __forceinline__ void gemm_phase(LAS unsigned char* lds, const bf16* gA, const bf16* gBt, const Sched& S, const Epi& E, const int wid) {
;     ...
;         if constexpr (ALIGN_EPI) { if (wr == 0) PG8_BAR; }
;         E(acc, cur, wr, wc, fr, fq);
;         if (!has_next) break;
; #pragma unroll
;         for (int a = 0; a < 2; ++a)
; #pragma unroll
;             for (int b = 0; b < 2; ++b)
; #pragma unroll
;                 for (int m = 0; m < 4; ++m)
; #pragma unroll
;                     for (int n = 0; n < 2; ++n) acc[a][b][m][n] = (f32x4){0.f, 0.f, 0.f, 0.f};
;         cur = nxt; cA = nA; cB = nB; ++ui;
;         if constexpr (ALIGN_EPI) { if (wr == 1) PG8_BAR; }
;     }
.LBB0_1297:
	s_cmp_lg_u32 s64, 0x100
	s_cbranch_scc1 .Lp5b_epi
	s_cmp_lg_u32 s42, 3
	s_cbranch_scc1 .Lp5b_epi
	s_cmp_gt_u32 s86, 63
	s_cbranch_scc1 .Lp5b_epi
	s_bfe_u32 s65, s86, 0x20003
	s_and_b32 s66, s86, 7
	s_lshl_b32 s66, s66, 1
	s_bfe_u32 s67, s86, 0x10005
	s_add_i32 s66, s66, s67
	v_readlane_b32 s67, v249, 0
	v_lshlrev_b32_e32 v140, 4, v196
	s_nop 1
	s_lshl_b32 s68, s67, 10
	v_add_u32_e32 v140, s68, v140
	s_mul_i32 s68, s66, 3
	s_lshl_b32 s68, s68, 18
	s_add_u32 s70, s22, s68
	s_addc_u32 s71, s23, 0
	s_add_u32 s70, s70, 0xc00000
	s_addc_u32 s71, s71, 0
	s_cmp_eq_u32 s65, 0
	s_cbranch_scc1 .Lp5b_cons
	s_add_i32 s68, s65, -1
	s_lshl_b32 s68, s68, 18
	s_add_u32 s70, s70, s68
	s_addc_u32 s71, s71, 0
	s_nop 7
	global_store_dwordx4 v140, v[0:3], s[70:71] sc0 sc1
	s_add_u32 s70, s70, 0x2000
	s_addc_u32 s71, s71, 0
	global_store_dwordx4 v140, v[4:7], s[70:71] sc0 sc1
	s_add_u32 s70, s70, 0x2000
	s_addc_u32 s71, s71, 0
	global_store_dwordx4 v140, v[8:11], s[70:71] sc0 sc1
	s_add_u32 s70, s70, 0x2000
	s_addc_u32 s71, s71, 0
	global_store_dwordx4 v140, v[12:15], s[70:71] sc0 sc1
	s_add_u32 s70, s70, 0x2000
	s_addc_u32 s71, s71, 0
	global_store_dwordx4 v140, v[16:19], s[70:71] sc0 sc1
	s_add_u32 s70, s70, 0x2000
	s_addc_u32 s71, s71, 0
	global_store_dwordx4 v140, v[20:23], s[70:71] sc0 sc1
	s_add_u32 s70, s70, 0x2000
	s_addc_u32 s71, s71, 0
	global_store_dwordx4 v140, v[24:27], s[70:71] sc0 sc1
	s_add_u32 s70, s70, 0x2000
	s_addc_u32 s71, s71, 0
	global_store_dwordx4 v140, v[28:31], s[70:71] sc0 sc1
	s_add_u32 s70, s70, 0x2000
	s_addc_u32 s71, s71, 0
	global_store_dwordx4 v140, v[32:35], s[70:71] sc0 sc1
	s_add_u32 s70, s70, 0x2000
	s_addc_u32 s71, s71, 0
	global_store_dwordx4 v140, v[36:39], s[70:71] sc0 sc1
	s_add_u32 s70, s70, 0x2000
	s_addc_u32 s71, s71, 0
	global_store_dwordx4 v140, v[40:43], s[70:71] sc0 sc1
	s_add_u32 s70, s70, 0x2000
	s_addc_u32 s71, s71, 0
	global_store_dwordx4 v140, v[44:47], s[70:71] sc0 sc1
	s_add_u32 s70, s70, 0x2000
	s_addc_u32 s71, s71, 0
	global_store_dwordx4 v140, v[48:51], s[70:71] sc0 sc1
	s_add_u32 s70, s70, 0x2000
	s_addc_u32 s71, s71, 0
	global_store_dwordx4 v140, v[52:55], s[70:71] sc0 sc1
	s_add_u32 s70, s70, 0x2000
	s_addc_u32 s71, s71, 0
	global_store_dwordx4 v140, v[56:59], s[70:71] sc0 sc1
	s_add_u32 s70, s70, 0x2000
	s_addc_u32 s71, s71, 0
	global_store_dwordx4 v140, v[60:63], s[70:71] sc0 sc1
	s_add_u32 s70, s70, 0x2000
	s_addc_u32 s71, s71, 0
	global_store_dwordx4 v140, v[64:67], s[70:71] sc0 sc1
	s_add_u32 s70, s70, 0x2000
	s_addc_u32 s71, s71, 0
	global_store_dwordx4 v140, v[68:71], s[70:71] sc0 sc1
	s_add_u32 s70, s70, 0x2000
	s_addc_u32 s71, s71, 0
	global_store_dwordx4 v140, v[72:75], s[70:71] sc0 sc1
	s_add_u32 s70, s70, 0x2000
	s_addc_u32 s71, s71, 0
	global_store_dwordx4 v140, v[76:79], s[70:71] sc0 sc1
	s_add_u32 s70, s70, 0x2000
	s_addc_u32 s71, s71, 0
	global_store_dwordx4 v140, v[80:83], s[70:71] sc0 sc1
	s_add_u32 s70, s70, 0x2000
	s_addc_u32 s71, s71, 0
	global_store_dwordx4 v140, v[84:87], s[70:71] sc0 sc1
	s_add_u32 s70, s70, 0x2000
	s_addc_u32 s71, s71, 0
	global_store_dwordx4 v140, v[88:91], s[70:71] sc0 sc1
	s_add_u32 s70, s70, 0x2000
	s_addc_u32 s71, s71, 0
	global_store_dwordx4 v140, v[92:95], s[70:71] sc0 sc1
	s_add_u32 s70, s70, 0x2000
	s_addc_u32 s71, s71, 0
	global_store_dwordx4 v140, v[96:99], s[70:71] sc0 sc1
	s_add_u32 s70, s70, 0x2000
	s_addc_u32 s71, s71, 0
	global_store_dwordx4 v140, v[100:103], s[70:71] sc0 sc1
	s_add_u32 s70, s70, 0x2000
	s_addc_u32 s71, s71, 0
	global_store_dwordx4 v140, v[104:107], s[70:71] sc0 sc1
	s_add_u32 s70, s70, 0x2000
	s_addc_u32 s71, s71, 0
	global_store_dwordx4 v140, v[108:111], s[70:71] sc0 sc1
	s_add_u32 s70, s70, 0x2000
	s_addc_u32 s71, s71, 0
	global_store_dwordx4 v140, v[112:115], s[70:71] sc0 sc1
	s_add_u32 s70, s70, 0x2000
	s_addc_u32 s71, s71, 0
	global_store_dwordx4 v140, v[116:119], s[70:71] sc0 sc1
	s_add_u32 s70, s70, 0x2000
	s_addc_u32 s71, s71, 0
	global_store_dwordx4 v140, v[120:123], s[70:71] sc0 sc1
	s_add_u32 s70, s70, 0x2000
	s_addc_u32 s71, s71, 0
	global_store_dwordx4 v140, v[124:127], s[70:71] sc0 sc1
	s_waitcnt vmcnt(0)
	s_lshl_b32 s68, s66, 2
	s_add_i32 s68, s68, s65
	s_lshl_b32 s68, s68, 2
	v_mov_b32_e32 v141, s68
	v_mov_b32_e32 v142, 1
	s_mov_b64 s[72:73], exec
	s_mov_b64 exec, 1
	global_atomic_add v141, v142, s[20:21] offset:3200
	s_mov_b64 exec, s[72:73]
	s_branch .LBB0_1300

; __global__ void __launch_bounds__(NWAVES * 64, 2) mega_fwd(Args args) {
	.amdhsa_kernel _Z8mega_fwd4Args
		.amdhsa_group_segment_fixed_size 0
		.amdhsa_private_segment_fixed_size 0
		.amdhsa_kernarg_size 440
		.amdhsa_user_sgpr_count 2
		.amdhsa_user_sgpr_dispatch_ptr 0
		.amdhsa_user_sgpr_queue_ptr 0
		.amdhsa_user_sgpr_kernarg_segment_ptr 1
		.amdhsa_user_sgpr_dispatch_id 0
		.amdhsa_user_sgpr_kernarg_preload_length 0
		.amdhsa_user_sgpr_kernarg_preload_offset 0
		.amdhsa_user_sgpr_private_segment_size 0
		.amdhsa_uses_dynamic_stack 0
		.amdhsa_enable_private_segment 0
		.amdhsa_system_sgpr_workgroup_id_x 1
		.amdhsa_system_sgpr_workgroup_id_y 0
		.amdhsa_system_sgpr_workgroup_id_z 0
		.amdhsa_system_sgpr_workgroup_info 0
		.amdhsa_system_vgpr_workitem_id 2
		.amdhsa_next_free_vgpr 256
		.amdhsa_next_free_sgpr 98
		.amdhsa_accum_offset 256
		.amdhsa_reserve_vcc 1
		.amdhsa_float_round_mode_32 0
		.amdhsa_float_round_mode_16_64 0
		.amdhsa_float_denorm_mode_32 3
		.amdhsa_float_denorm_mode_16_64 3
		.amdhsa_dx10_clamp 1
		.amdhsa_ieee_mode 1
		.amdhsa_fp16_overflow 0
		.amdhsa_tg_split 0
		.amdhsa_exception_fp_ieee_invalid_op 0
		.amdhsa_exception_fp_denorm_src 0
		.amdhsa_exception_fp_ieee_div_zero 0
		.amdhsa_exception_fp_ieee_overflow 0
		.amdhsa_exception_fp_ieee_underflow 0
		.amdhsa_exception_fp_ieee_inexact 0
		.amdhsa_exception_int_div_zero 0
	.end_amdhsa_kernel

; __global__ void __launch_bounds__(NWAVES * 64, 2) mega_fwd(Args args) {
amdhsa.kernels:
  - .agpr_count:     0
    .args:
      - .offset:         0
        .size:           184
        .value_kind:     by_value
      - .offset:         184
        .size:           4
        .value_kind:     hidden_block_count_x
      - .offset:         188
        .size:           4
        .value_kind:     hidden_block_count_y
      - .offset:         192
        .size:           4
        .value_kind:     hidden_block_count_z
      - .offset:         196
        .size:           2
        .value_kind:     hidden_group_size_x
      - .offset:         198
        .size:           2
        .value_kind:     hidden_group_size_y
      - .offset:         200
        .size:           2
        .value_kind:     hidden_group_size_z
      - .offset:         202
        .size:           2
        .value_kind:     hidden_remainder_x
      - .offset:         204
        .size:           2
        .value_kind:     hidden_remainder_y
      - .offset:         206
        .size:           2
        .value_kind:     hidden_remainder_z
      - .offset:         224
        .size:           8
        .value_kind:     hidden_global_offset_x
      - .offset:         232
        .size:           8
        .value_kind:     hidden_global_offset_y
      - .offset:         240
        .size:           8
        .value_kind:     hidden_global_offset_z
      - .offset:         248
        .size:           2
        .value_kind:     hidden_grid_dims
      - .offset:         272
        .size:           8
        .value_kind:     hidden_multigrid_sync_arg
      - .offset:         304
        .size:           4
        .value_kind:     hidden_dynamic_lds_size
    .group_segment_fixed_size: 0
    .kernarg_segment_align: 8
    .kernarg_segment_size: 440
    .language:       OpenCL C
    .language_version:
      - 2
      - 0
    .max_flat_workgroup_size: 512
    .name:           _Z8mega_fwd4Args
    .private_segment_fixed_size: 0
    .sgpr_count:     104
    .sgpr_spill_count: 70
    .symbol:         _Z8mega_fwd4Args.kd
    .uniform_work_group_size: 1
    .uses_dynamic_stack: false
    .vgpr_count:     256
    .vgpr_spill_count: 0
    .wavefront_size: 64
